# up-GEMM epilogue: hoist the 8 per-row ss2 loads ahead of the stores; drop vmcnt(0) waits that drained stores
# baseline (speedup 1.0000x reference)
.LBB0_1099:
	s_ashr_i32 s17, s4, 4
	s_mul_hi_i32 s19, s17, 0x5800
	s_mulk_i32 s17, 0x5800
	s_add_u32 s17, s48, s17
	s_addc_u32 s19, s49, s19
	s_lshl_b32 s24, s60, 8
	s_ashr_i32 s25, s24, 31
	s_lshl_b64 s[26:27], s[24:25], 2
	s_add_u32 s17, s17, s26
	s_addc_u32 s19, s19, s27
	s_lshl_b32 s26, s43, 2
	s_add_u32 s26, s17, s26
	s_addc_u32 s27, s19, 0
	s_lshl_b32 s17, s4, 8
	v_add_u32_e32 v168, s17, v157
	v_ashrrev_i32_e32 v169, 31, v168
	v_lshl_add_u64 v[128:129], v[168:169], 2, s[12:13]
	global_load_dword v169, v[128:129], off
	global_load_dword v191, v[128:129], off offset:64
	global_load_dword v192, v[128:129], off offset:128
	global_load_dword v193, v[128:129], off offset:192
	global_load_dword v194, v[128:129], off offset:512
	global_load_dword v195, v[128:129], off offset:576
	global_load_dword v196, v[128:129], off offset:640
	global_load_dword v197, v[128:129], off offset:704
	v_lshlrev_b32_e32 v128, 2, v156
	global_load_dwordx4 v[140:143], v128, s[26:27]
	global_load_dwordx4 v[136:139], v128, s[26:27] offset:16
	global_load_dwordx4 v[132:135], v128, s[26:27] offset:512
	s_nop 0
	global_load_dwordx4 v[128:131], v128, s[26:27] offset:528
	v_mov_b64_e32 v[166:167], s[14:15]
	s_lshl_b64 s[24:25], s[24:25], 1
	v_mad_i64_i32 v[180:181], s[26:27], v168, s64, v[166:167]
	s_lshl_b32 s4, s43, 1
	v_lshl_add_u64 v[180:181], v[180:181], 0, s[24:25]
	v_lshlrev_b32_e32 v154, 1, v156
	v_add_u32_e32 v178, s17, v171
	v_lshl_add_u64 v[180:181], v[180:181], 0, s[4:5]
	v_ashrrev_i32_e32 v179, 31, v178
	v_lshl_add_u64 v[180:181], v[180:181], 0, v[154:155]
	v_lshl_add_u64 v[186:187], v[178:179], 2, s[12:13]
	s_andn2_b64 vcc, exec, s[2:3]
	s_waitcnt vmcnt(0)
	v_fmamk_f32 v169, v169, 0x3a800000, v177
	v_rsq_f32_e32 v182, v169
	s_nop 0
	v_pk_fma_f32 v[126:127], v[126:127], v[182:183], v[142:143] op_sel_hi:[1,0,1]
	v_pk_fma_f32 v[124:125], v[124:125], v[182:183], v[140:141] op_sel_hi:[1,0,1]
	v_pk_fma_f32 v[122:123], v[122:123], v[182:183], v[138:139] op_sel_hi:[1,0,1]
	v_pk_fma_f32 v[120:121], v[120:121], v[182:183], v[136:137] op_sel_hi:[1,0,1]
	v_pk_fma_f32 v[118:119], v[118:119], v[182:183], v[134:135] op_sel_hi:[1,0,1]
	v_pk_fma_f32 v[116:117], v[116:117], v[182:183], v[132:133] op_sel_hi:[1,0,1]
	v_pk_fma_f32 v[188:189], v[114:115], v[182:183], v[130:131] op_sel_hi:[1,0,1]
	v_pk_fma_f32 v[182:183], v[112:113], v[182:183], v[128:129] op_sel_hi:[1,0,1]
	v_cvt_pk_bf16_f32 v112, v124, v125
	v_cvt_pk_bf16_f32 v113, v126, v127
	v_cvt_pk_bf16_f32 v114, v120, v121
	v_cvt_pk_bf16_f32 v115, v122, v123
	v_cvt_pk_bf16_f32 v116, v116, v117
	v_cvt_pk_bf16_f32 v117, v118, v119
	v_cvt_pk_bf16_f32 v118, v182, v183
	v_cvt_pk_bf16_f32 v119, v188, v189
	global_store_dwordx4 v[180:181], v[112:115], off
	global_store_dwordx4 v[180:181], v[116:119], off offset:256
	s_nop 1
	v_mov_b32_e32 v116, v191
	v_mad_i64_i32 v[114:115], s[26:27], v178, s64, v[166:167]
	v_lshl_add_u64 v[114:115], v[114:115], 0, s[24:25]
	v_add_u32_e32 v112, s17, v172
	v_lshl_add_u64 v[114:115], v[114:115], 0, s[4:5]
	v_ashrrev_i32_e32 v113, 31, v112
	v_lshl_add_u64 v[114:115], v[114:115], 0, v[154:155]
	v_lshl_add_u64 v[118:119], v[112:113], 2, s[12:13]
	v_fmamk_f32 v116, v116, 0x3a800000, v177
	v_rsq_f32_e32 v116, v116
	s_nop 0
	v_pk_fma_f32 v[110:111], v[110:111], v[116:117], v[142:143] op_sel_hi:[1,0,1]
	v_pk_fma_f32 v[108:109], v[108:109], v[116:117], v[140:141] op_sel_hi:[1,0,1]
	v_pk_fma_f32 v[106:107], v[106:107], v[116:117], v[138:139] op_sel_hi:[1,0,1]
	v_pk_fma_f32 v[104:105], v[104:105], v[116:117], v[136:137] op_sel_hi:[1,0,1]
	v_pk_fma_f32 v[102:103], v[102:103], v[116:117], v[134:135] op_sel_hi:[1,0,1]
	v_pk_fma_f32 v[100:101], v[100:101], v[116:117], v[132:133] op_sel_hi:[1,0,1]
	v_pk_fma_f32 v[120:121], v[98:99], v[116:117], v[130:131] op_sel_hi:[1,0,1]
	v_pk_fma_f32 v[116:117], v[96:97], v[116:117], v[128:129] op_sel_hi:[1,0,1]
	v_cvt_pk_bf16_f32 v96, v108, v109
	v_cvt_pk_bf16_f32 v97, v110, v111
	v_cvt_pk_bf16_f32 v98, v104, v105
	v_cvt_pk_bf16_f32 v99, v106, v107
	v_cvt_pk_bf16_f32 v100, v100, v101
	v_cvt_pk_bf16_f32 v101, v102, v103
	v_cvt_pk_bf16_f32 v102, v116, v117
	v_cvt_pk_bf16_f32 v103, v120, v121
	global_store_dwordx4 v[114:115], v[96:99], off
	global_store_dwordx4 v[114:115], v[100:103], off offset:256
	s_nop 1
	v_mov_b32_e32 v100, v192
	v_mad_i64_i32 v[98:99], s[26:27], v112, s64, v[166:167]
	v_lshl_add_u64 v[98:99], v[98:99], 0, s[24:25]
	v_add_u32_e32 v96, s17, v173
	v_lshl_add_u64 v[98:99], v[98:99], 0, s[4:5]
	v_ashrrev_i32_e32 v97, 31, v96
	v_lshl_add_u64 v[98:99], v[98:99], 0, v[154:155]
	v_lshl_add_u64 v[102:103], v[96:97], 2, s[12:13]
	v_fmamk_f32 v100, v100, 0x3a800000, v177
	v_rsq_f32_e32 v100, v100
	s_nop 0
	v_pk_fma_f32 v[94:95], v[94:95], v[100:101], v[142:143] op_sel_hi:[1,0,1]
	v_pk_fma_f32 v[92:93], v[92:93], v[100:101], v[140:141] op_sel_hi:[1,0,1]
	v_pk_fma_f32 v[90:91], v[90:91], v[100:101], v[138:139] op_sel_hi:[1,0,1]
	v_pk_fma_f32 v[88:89], v[88:89], v[100:101], v[136:137] op_sel_hi:[1,0,1]
	v_pk_fma_f32 v[86:87], v[86:87], v[100:101], v[134:135] op_sel_hi:[1,0,1]
	v_pk_fma_f32 v[84:85], v[84:85], v[100:101], v[132:133] op_sel_hi:[1,0,1]
	v_pk_fma_f32 v[104:105], v[82:83], v[100:101], v[130:131] op_sel_hi:[1,0,1]
	v_pk_fma_f32 v[100:101], v[80:81], v[100:101], v[128:129] op_sel_hi:[1,0,1]
	v_cvt_pk_bf16_f32 v80, v92, v93
	v_cvt_pk_bf16_f32 v81, v94, v95
	v_cvt_pk_bf16_f32 v82, v88, v89
	v_cvt_pk_bf16_f32 v83, v90, v91
	v_cvt_pk_bf16_f32 v84, v84, v85
	v_cvt_pk_bf16_f32 v85, v86, v87
	v_cvt_pk_bf16_f32 v86, v100, v101
	v_cvt_pk_bf16_f32 v87, v104, v105
	global_store_dwordx4 v[98:99], v[80:83], off
	global_store_dwordx4 v[98:99], v[84:87], off offset:256
	s_nop 1
	v_mov_b32_e32 v84, v193
	v_mad_i64_i32 v[80:81], s[26:27], v96, s64, v[166:167]
	v_lshl_add_u64 v[80:81], v[80:81], 0, s[24:25]
	v_add_u32_e32 v82, 0x80, v168
	v_lshl_add_u64 v[80:81], v[80:81], 0, s[4:5]
	v_ashrrev_i32_e32 v83, 31, v82
	v_lshl_add_u64 v[80:81], v[80:81], 0, v[154:155]
	v_lshl_add_u64 v[86:87], v[82:83], 2, s[12:13]
	v_fmamk_f32 v84, v84, 0x3a800000, v177
	v_rsq_f32_e32 v84, v84
	s_nop 0
	v_pk_fma_f32 v[78:79], v[78:79], v[84:85], v[142:143] op_sel_hi:[1,0,1]
	v_pk_fma_f32 v[76:77], v[76:77], v[84:85], v[140:141] op_sel_hi:[1,0,1]
	v_pk_fma_f32 v[74:75], v[74:75], v[84:85], v[138:139] op_sel_hi:[1,0,1]
	v_pk_fma_f32 v[72:73], v[72:73], v[84:85], v[136:137] op_sel_hi:[1,0,1]
	v_pk_fma_f32 v[70:71], v[70:71], v[84:85], v[134:135] op_sel_hi:[1,0,1]
	v_pk_fma_f32 v[68:69], v[68:69], v[84:85], v[132:133] op_sel_hi:[1,0,1]
	v_pk_fma_f32 v[88:89], v[66:67], v[84:85], v[130:131] op_sel_hi:[1,0,1]
	v_pk_fma_f32 v[84:85], v[64:65], v[84:85], v[128:129] op_sel_hi:[1,0,1]
	v_cvt_pk_bf16_f32 v64, v76, v77
	v_cvt_pk_bf16_f32 v65, v78, v79
	v_cvt_pk_bf16_f32 v66, v72, v73
	v_cvt_pk_bf16_f32 v67, v74, v75
	v_cvt_pk_bf16_f32 v68, v68, v69
	v_cvt_pk_bf16_f32 v69, v70, v71
	v_cvt_pk_bf16_f32 v70, v84, v85
	v_cvt_pk_bf16_f32 v71, v88, v89
	global_store_dwordx4 v[80:81], v[64:67], off
	global_store_dwordx4 v[80:81], v[68:71], off offset:256
	s_nop 1
	v_mov_b32_e32 v68, v194
	v_mad_i64_i32 v[66:67], s[26:27], v82, s64, v[166:167]
	v_lshl_add_u64 v[66:67], v[66:67], 0, s[24:25]
	v_add_u32_e32 v64, 0x90, v168
	v_lshl_add_u64 v[66:67], v[66:67], 0, s[4:5]
	v_ashrrev_i32_e32 v65, 31, v64
	v_lshl_add_u64 v[66:67], v[66:67], 0, v[154:155]
	v_lshl_add_u64 v[70:71], v[64:65], 2, s[12:13]
	v_fmamk_f32 v68, v68, 0x3a800000, v177
	v_rsq_f32_e32 v68, v68
	s_nop 0
	v_pk_fma_f32 v[62:63], v[62:63], v[68:69], v[142:143] op_sel_hi:[1,0,1]
	v_pk_fma_f32 v[60:61], v[60:61], v[68:69], v[140:141] op_sel_hi:[1,0,1]
	v_pk_fma_f32 v[58:59], v[58:59], v[68:69], v[138:139] op_sel_hi:[1,0,1]
	v_pk_fma_f32 v[56:57], v[56:57], v[68:69], v[136:137] op_sel_hi:[1,0,1]
	v_pk_fma_f32 v[54:55], v[54:55], v[68:69], v[134:135] op_sel_hi:[1,0,1]
	v_pk_fma_f32 v[52:53], v[52:53], v[68:69], v[132:133] op_sel_hi:[1,0,1]
	v_pk_fma_f32 v[72:73], v[50:51], v[68:69], v[130:131] op_sel_hi:[1,0,1]
	v_pk_fma_f32 v[68:69], v[48:49], v[68:69], v[128:129] op_sel_hi:[1,0,1]
	v_cvt_pk_bf16_f32 v48, v60, v61
	v_cvt_pk_bf16_f32 v49, v62, v63
	v_cvt_pk_bf16_f32 v50, v56, v57
	v_cvt_pk_bf16_f32 v51, v58, v59
	v_cvt_pk_bf16_f32 v52, v52, v53
	v_cvt_pk_bf16_f32 v53, v54, v55
	v_cvt_pk_bf16_f32 v54, v68, v69
	v_cvt_pk_bf16_f32 v55, v72, v73
	global_store_dwordx4 v[66:67], v[48:51], off
	global_store_dwordx4 v[66:67], v[52:55], off offset:256
	s_nop 1
	v_mov_b32_e32 v52, v195
	v_mad_i64_i32 v[50:51], s[26:27], v64, s64, v[166:167]
	v_lshl_add_u64 v[50:51], v[50:51], 0, s[24:25]
	v_add_u32_e32 v48, 0xa0, v168
	v_lshl_add_u64 v[50:51], v[50:51], 0, s[4:5]
	v_ashrrev_i32_e32 v49, 31, v48
	v_lshl_add_u64 v[50:51], v[50:51], 0, v[154:155]
	v_lshl_add_u64 v[54:55], v[48:49], 2, s[12:13]
	v_fmamk_f32 v52, v52, 0x3a800000, v177
	v_rsq_f32_e32 v52, v52
	s_nop 0
	v_pk_fma_f32 v[46:47], v[46:47], v[52:53], v[142:143] op_sel_hi:[1,0,1]
	v_pk_fma_f32 v[44:45], v[44:45], v[52:53], v[140:141] op_sel_hi:[1,0,1]
	v_pk_fma_f32 v[42:43], v[42:43], v[52:53], v[138:139] op_sel_hi:[1,0,1]
	v_pk_fma_f32 v[40:41], v[40:41], v[52:53], v[136:137] op_sel_hi:[1,0,1]
	v_pk_fma_f32 v[38:39], v[38:39], v[52:53], v[134:135] op_sel_hi:[1,0,1]
	v_pk_fma_f32 v[36:37], v[36:37], v[52:53], v[132:133] op_sel_hi:[1,0,1]
	v_pk_fma_f32 v[56:57], v[34:35], v[52:53], v[130:131] op_sel_hi:[1,0,1]
	v_pk_fma_f32 v[52:53], v[32:33], v[52:53], v[128:129] op_sel_hi:[1,0,1]
	v_cvt_pk_bf16_f32 v32, v44, v45
	v_cvt_pk_bf16_f32 v33, v46, v47
	v_cvt_pk_bf16_f32 v34, v40, v41
	v_cvt_pk_bf16_f32 v35, v42, v43
	v_cvt_pk_bf16_f32 v36, v36, v37
	v_cvt_pk_bf16_f32 v37, v38, v39
	v_cvt_pk_bf16_f32 v38, v52, v53
	v_cvt_pk_bf16_f32 v39, v56, v57
	global_store_dwordx4 v[50:51], v[32:35], off
	global_store_dwordx4 v[50:51], v[36:39], off offset:256
	s_nop 1
	v_mov_b32_e32 v36, v196
	v_mad_i64_i32 v[34:35], s[26:27], v48, s64, v[166:167]
	v_lshl_add_u64 v[34:35], v[34:35], 0, s[24:25]
	v_add_u32_e32 v32, 0xb0, v168
	v_lshl_add_u64 v[34:35], v[34:35], 0, s[4:5]
	v_ashrrev_i32_e32 v33, 31, v32
	v_lshl_add_u64 v[34:35], v[34:35], 0, v[154:155]
	v_lshl_add_u64 v[38:39], v[32:33], 2, s[12:13]
	v_fmamk_f32 v36, v36, 0x3a800000, v177
	v_rsq_f32_e32 v36, v36
	s_nop 0
	v_pk_fma_f32 v[30:31], v[30:31], v[36:37], v[142:143] op_sel_hi:[1,0,1]
	v_pk_fma_f32 v[28:29], v[28:29], v[36:37], v[140:141] op_sel_hi:[1,0,1]
	v_pk_fma_f32 v[26:27], v[26:27], v[36:37], v[138:139] op_sel_hi:[1,0,1]
	v_pk_fma_f32 v[24:25], v[24:25], v[36:37], v[136:137] op_sel_hi:[1,0,1]
	v_pk_fma_f32 v[22:23], v[22:23], v[36:37], v[134:135] op_sel_hi:[1,0,1]
	v_pk_fma_f32 v[20:21], v[20:21], v[36:37], v[132:133] op_sel_hi:[1,0,1]
	v_pk_fma_f32 v[40:41], v[18:19], v[36:37], v[130:131] op_sel_hi:[1,0,1]
	v_pk_fma_f32 v[36:37], v[16:17], v[36:37], v[128:129] op_sel_hi:[1,0,1]
	v_cvt_pk_bf16_f32 v16, v28, v29
	v_cvt_pk_bf16_f32 v17, v30, v31
	v_cvt_pk_bf16_f32 v18, v24, v25
	v_cvt_pk_bf16_f32 v19, v26, v27
	v_cvt_pk_bf16_f32 v20, v20, v21
	v_cvt_pk_bf16_f32 v21, v22, v23
	v_cvt_pk_bf16_f32 v22, v36, v37
	v_cvt_pk_bf16_f32 v23, v40, v41
	global_store_dwordx4 v[34:35], v[16:19], off
	global_store_dwordx4 v[34:35], v[20:23], off offset:256
	s_nop 1
	v_mov_b32_e32 v18, v197
	v_mad_i64_i32 v[16:17], s[2:3], v32, s64, v[166:167]
	v_lshl_add_u64 v[16:17], v[16:17], 0, s[24:25]
	v_lshl_add_u64 v[16:17], v[16:17], 0, s[4:5]
	v_lshl_add_u64 v[16:17], v[16:17], 0, v[154:155]
	s_mov_b64 s[2:3], -1
	v_fmamk_f32 v18, v18, 0x3a800000, v177
	v_rsq_f32_e32 v18, v18
	s_nop 0
	v_pk_fma_f32 v[14:15], v[14:15], v[18:19], v[142:143] op_sel_hi:[1,0,1]
	v_pk_fma_f32 v[12:13], v[12:13], v[18:19], v[140:141] op_sel_hi:[1,0,1]
	v_pk_fma_f32 v[10:11], v[10:11], v[18:19], v[138:139] op_sel_hi:[1,0,1]
	v_pk_fma_f32 v[8:9], v[8:9], v[18:19], v[136:137] op_sel_hi:[1,0,1]
	v_pk_fma_f32 v[6:7], v[6:7], v[18:19], v[134:135] op_sel_hi:[1,0,1]
	v_pk_fma_f32 v[4:5], v[4:5], v[18:19], v[132:133] op_sel_hi:[1,0,1]
	v_pk_fma_f32 v[20:21], v[2:3], v[18:19], v[130:131] op_sel_hi:[1,0,1]
	v_pk_fma_f32 v[18:19], v[0:1], v[18:19], v[128:129] op_sel_hi:[1,0,1]
	v_cvt_pk_bf16_f32 v0, v12, v13
	v_cvt_pk_bf16_f32 v1, v14, v15
	v_cvt_pk_bf16_f32 v2, v8, v9
	v_cvt_pk_bf16_f32 v3, v10, v11
	v_cvt_pk_bf16_f32 v4, v4, v5
	v_cvt_pk_bf16_f32 v5, v6, v7
	v_cvt_pk_bf16_f32 v6, v18, v19
	v_cvt_pk_bf16_f32 v7, v20, v21
	global_store_dwordx4 v[16:17], v[0:3], off
	global_store_dwordx4 v[16:17], v[4:7], off offset:256
	s_cbranch_vccnz .LBB0_1092
	s_andn2_b64 vcc, exec, s[6:7]
	s_cbranch_vccnz .LBB0_1091
	s_barrier
	s_branch .LBB0_1091
